# v104 + barrier #0: early arrivers sleep longer between census polls (s_sleep 12)
# speedup vs baseline: 1.0039x; 1.0039x over previous
; __device__ __forceinline__ unsigned xb_ld(unsigned* p)              { return __hip_atomic_load(p, __ATOMIC_RELAXED, __HIP_MEMORY_SCOPE_AGENT); }
; __device__ __forceinline__ void xcd_barrier_complete(unsigned* bar, unsigned x, unsigned& nloc, unsigned& nx) {
;     const unsigned G = gridDim.x * gridDim.y * gridDim.z;
;     unsigned sum, cnt, mine, sp = 0u;
;     for (;;) {
;         sum = 0u; cnt = 0u; mine = 0u;
; #pragma unroll
;         for (unsigned j = 0; j < 16; ++j) { const unsigned c = xb_ld(&bar[XB_XCNT(j)]); sum += c; cnt += (c > 0u) ? 1u : 0u; mine = (j == x) ? c : mine; }
;         if (sum == G) break;
;         __builtin_amdgcn_s_sleep(1);
;         if ((++sp & 255u) == 0u) { if (xb_ld(&bar[XB_TMO])) break; if (sp > XB_SPIN_CAP) { atomicAdd(&bar[XB_TMO], 1u); break; } }
;     }
;     nloc = mine > 0u ? mine : 1u; nx = cnt > 0u ? cnt : 1u;
; }
.Lgb0_census:
	global_load_dword v8, v0, s[84:85] offset:1024 sc1
	global_load_dword v9, v0, s[84:85] offset:1280 sc1
	global_load_dword v10, v0, s[84:85] offset:1536 sc1
	global_load_dword v11, v0, s[84:85] offset:1792 sc1
	global_load_dword v12, v0, s[84:85] offset:2048 sc1
	global_load_dword v13, v0, s[84:85] offset:2304 sc1
	global_load_dword v14, v0, s[84:85] offset:2560 sc1
	global_load_dword v15, v0, s[84:85] offset:2816 sc1
	global_load_dword v16, v0, s[84:85] offset:3072 sc1
	global_load_dword v17, v0, s[84:85] offset:3328 sc1
	global_load_dword v18, v0, s[84:85] offset:3584 sc1
	global_load_dword v19, v0, s[84:85] offset:3840 sc1
	global_load_dword v20, v5, s[84:85] offset:0 sc1
	global_load_dword v21, v5, s[84:85] offset:256 sc1
	global_load_dword v22, v5, s[84:85] offset:512 sc1
	global_load_dword v23, v5, s[84:85] offset:768 sc1
	s_waitcnt vmcnt(0)
	s_mov_b32 s9, 0
	s_mov_b32 s10, 0
	s_mov_b32 s11, 0
	v_readfirstlane_b32 s6, v8
	s_add_u32 s9, s9, s6
	s_cmp_lg_u32 s6, 0
	s_addc_u32 s10, s10, 0
	s_cmp_eq_u32 s3, 0
	s_cselect_b32 s11, s6, s11
	v_readfirstlane_b32 s6, v9
	s_add_u32 s9, s9, s6
	s_cmp_lg_u32 s6, 0
	s_addc_u32 s10, s10, 0
	s_cmp_eq_u32 s3, 1
	s_cselect_b32 s11, s6, s11
	v_readfirstlane_b32 s6, v10
	s_add_u32 s9, s9, s6
	s_cmp_lg_u32 s6, 0
	s_addc_u32 s10, s10, 0
	s_cmp_eq_u32 s3, 2
	s_cselect_b32 s11, s6, s11
	v_readfirstlane_b32 s6, v11
	s_add_u32 s9, s9, s6
	s_cmp_lg_u32 s6, 0
	s_addc_u32 s10, s10, 0
	s_cmp_eq_u32 s3, 3
	s_cselect_b32 s11, s6, s11
	v_readfirstlane_b32 s6, v12
	s_add_u32 s9, s9, s6
	s_cmp_lg_u32 s6, 0
	s_addc_u32 s10, s10, 0
	s_cmp_eq_u32 s3, 4
	s_cselect_b32 s11, s6, s11
	v_readfirstlane_b32 s6, v13
	s_add_u32 s9, s9, s6
	s_cmp_lg_u32 s6, 0
	s_addc_u32 s10, s10, 0
	s_cmp_eq_u32 s3, 5
	s_cselect_b32 s11, s6, s11
	v_readfirstlane_b32 s6, v14
	s_add_u32 s9, s9, s6
	s_cmp_lg_u32 s6, 0
	s_addc_u32 s10, s10, 0
	s_cmp_eq_u32 s3, 6
	s_cselect_b32 s11, s6, s11
	v_readfirstlane_b32 s6, v15
	s_add_u32 s9, s9, s6
	s_cmp_lg_u32 s6, 0
	s_addc_u32 s10, s10, 0
	s_cmp_eq_u32 s3, 7
	s_cselect_b32 s11, s6, s11
	v_readfirstlane_b32 s6, v16
	s_add_u32 s9, s9, s6
	s_cmp_lg_u32 s6, 0
	s_addc_u32 s10, s10, 0
	s_cmp_eq_u32 s3, 8
	s_cselect_b32 s11, s6, s11
	v_readfirstlane_b32 s6, v17
	s_add_u32 s9, s9, s6
	s_cmp_lg_u32 s6, 0
	s_addc_u32 s10, s10, 0
	s_cmp_eq_u32 s3, 9
	s_cselect_b32 s11, s6, s11
	v_readfirstlane_b32 s6, v18
	s_add_u32 s9, s9, s6
	s_cmp_lg_u32 s6, 0
	s_addc_u32 s10, s10, 0
	s_cmp_eq_u32 s3, 10
	s_cselect_b32 s11, s6, s11
	v_readfirstlane_b32 s6, v19
	s_add_u32 s9, s9, s6
	s_cmp_lg_u32 s6, 0
	s_addc_u32 s10, s10, 0
	s_cmp_eq_u32 s3, 11
	s_cselect_b32 s11, s6, s11
	v_readfirstlane_b32 s6, v20
	s_add_u32 s9, s9, s6
	s_cmp_lg_u32 s6, 0
	s_addc_u32 s10, s10, 0
	s_cmp_eq_u32 s3, 12
	s_cselect_b32 s11, s6, s11
	v_readfirstlane_b32 s6, v21
	s_add_u32 s9, s9, s6
	s_cmp_lg_u32 s6, 0
	s_addc_u32 s10, s10, 0
	s_cmp_eq_u32 s3, 13
	s_cselect_b32 s11, s6, s11
	v_readfirstlane_b32 s6, v22
	s_add_u32 s9, s9, s6
	s_cmp_lg_u32 s6, 0
	s_addc_u32 s10, s10, 0
	s_cmp_eq_u32 s3, 14
	s_cselect_b32 s11, s6, s11
	v_readfirstlane_b32 s6, v23
	s_add_u32 s9, s9, s6
	s_cmp_lg_u32 s6, 0
	s_addc_u32 s10, s10, 0
	s_cmp_eq_u32 s3, 15
	s_cselect_b32 s11, s6, s11
	s_cmp_eq_u32 s9, s92
	s_cbranch_scc1 .Lgb0_census_ok
	s_sleep 12
	s_add_u32 s15, s15, 1
	s_cmp_lt_u32 s15, 0x10000
	s_cbranch_scc1 .Lgb0_census
